# A/B of the priority flips, other direction: an s_setprio 0 / s_setprio 1 window after every 8 MFMAs of the chain K-loop blocks (4 windows per 32-MFMA block instead of 2)
# baseline (speedup 1.0000x reference)
.LBB0_391:
	ds_read_b128 v[148:151], v144
	ds_read_b128 v[152:155], v144 offset:1024
	ds_read_b128 v[156:159], v144 offset:2048
	ds_read_b128 v[160:163], v144 offset:3072
	ds_read_b128 v[174:177], v145
	ds_read_b128 v[178:181], v145 offset:1024
	ds_read_b128 v[182:185], v145 offset:2048
	ds_read_b128 v[186:189], v145 offset:3072
	v_lshl_add_u64 v[236:237], v[142:143], 0, s[62:63]
	s_mov_b32 m0, s55
	v_lshl_add_u64 v[238:239], v[236:237], 0, s[44:45]
	ds_read_b128 v[190:193], v195
	ds_read_b128 v[208:211], v195 offset:1024
	ds_read_b128 v[212:215], v195 offset:2048
	ds_read_b128 v[216:219], v195 offset:3072
	ds_read_b128 v[220:223], v195 offset:4096
	ds_read_b128 v[224:227], v195 offset:5120
	ds_read_b128 v[228:231], v195 offset:6144
	ds_read_b128 v[232:235], v195 offset:7168
	global_load_lds_dwordx4 v[238:239], off
	v_lshl_add_u64 v[238:239], v[140:141], 0, s[62:63]
	v_lshl_add_u64 v[240:241], v[238:239], 0, s[44:45]
	s_mov_b32 m0, s97
	s_nop 0
	global_load_lds_dwordx4 v[240:241], off
	s_waitcnt vmcnt(8)
	s_waitcnt lgkmcnt(0)
	s_barrier
	s_setprio 1
	s_waitcnt lgkmcnt(0)
	v_mfma_f32_16x16x32_bf16 v[124:127], v[148:151], v[190:193], v[124:127]
	v_mfma_f32_16x16x32_bf16 v[120:123], v[156:159], v[190:193], v[120:123]
	v_mfma_f32_16x16x32_bf16 v[116:119], v[148:151], v[212:215], v[116:119]
	v_mfma_f32_16x16x32_bf16 v[112:115], v[156:159], v[212:215], v[112:115]
	v_mfma_f32_16x16x32_bf16 v[108:111], v[148:151], v[220:223], v[108:111]
	v_mfma_f32_16x16x32_bf16 v[104:107], v[156:159], v[220:223], v[104:107]
	v_mfma_f32_16x16x32_bf16 v[100:103], v[148:151], v[228:231], v[100:103]
	v_mfma_f32_16x16x32_bf16 v[96:99], v[156:159], v[228:231], v[96:99]
	s_setprio 0
	s_setprio 1
	v_mfma_f32_16x16x32_bf16 v[124:127], v[152:155], v[208:211], v[124:127]
	v_mfma_f32_16x16x32_bf16 v[120:123], v[160:163], v[208:211], v[120:123]
	v_mfma_f32_16x16x32_bf16 v[116:119], v[152:155], v[216:219], v[116:119]
	v_mfma_f32_16x16x32_bf16 v[112:115], v[160:163], v[216:219], v[112:115]
	v_mfma_f32_16x16x32_bf16 v[108:111], v[152:155], v[224:227], v[108:111]
	v_mfma_f32_16x16x32_bf16 v[104:107], v[160:163], v[224:227], v[104:107]
	v_mfma_f32_16x16x32_bf16 v[100:103], v[152:155], v[232:235], v[100:103]
	v_mfma_f32_16x16x32_bf16 v[96:99], v[160:163], v[232:235], v[96:99]
	s_setprio 0
	s_setprio 1
	v_mfma_f32_16x16x32_bf16 v[92:95], v[174:177], v[190:193], v[92:95]
	v_mfma_f32_16x16x32_bf16 v[88:91], v[182:185], v[190:193], v[88:91]
	v_mfma_f32_16x16x32_bf16 v[84:87], v[174:177], v[212:215], v[84:87]
	v_mfma_f32_16x16x32_bf16 v[80:83], v[182:185], v[212:215], v[80:83]
	v_mfma_f32_16x16x32_bf16 v[76:79], v[174:177], v[220:223], v[76:79]
	v_mfma_f32_16x16x32_bf16 v[72:75], v[182:185], v[220:223], v[72:75]
	v_mfma_f32_16x16x32_bf16 v[68:71], v[174:177], v[228:231], v[68:71]
	v_mfma_f32_16x16x32_bf16 v[64:67], v[182:185], v[228:231], v[64:67]
	s_setprio 0
	s_setprio 1
	v_mfma_f32_16x16x32_bf16 v[92:95], v[178:181], v[208:211], v[92:95]
	v_mfma_f32_16x16x32_bf16 v[88:91], v[186:189], v[208:211], v[88:91]
	v_mfma_f32_16x16x32_bf16 v[84:87], v[178:181], v[216:219], v[84:87]
	v_mfma_f32_16x16x32_bf16 v[80:83], v[186:189], v[216:219], v[80:83]
	v_mfma_f32_16x16x32_bf16 v[76:79], v[178:181], v[224:227], v[76:79]
	v_mfma_f32_16x16x32_bf16 v[72:75], v[186:189], v[224:227], v[72:75]
	v_mfma_f32_16x16x32_bf16 v[68:71], v[178:181], v[232:235], v[68:71]
	v_mfma_f32_16x16x32_bf16 v[64:67], v[186:189], v[232:235], v[64:67]
	s_setprio 0
	s_barrier
	v_lshl_add_u64 v[240:241], v[128:129], 0, s[62:63]
	s_mov_b32 m0, s2
	v_lshl_add_u64 v[242:243], v[240:241], 0, s[46:47]
	ds_read_b128 v[190:193], v195 offset:16384
	ds_read_b128 v[208:211], v195 offset:17408
	ds_read_b128 v[212:215], v195 offset:18432
	ds_read_b128 v[216:219], v195 offset:19456
	ds_read_b128 v[220:223], v195 offset:20480
	ds_read_b128 v[224:227], v195 offset:21504
	ds_read_b128 v[228:231], v195 offset:22528
	ds_read_b128 v[232:235], v195 offset:23552
	global_load_lds_dwordx4 v[242:243], off
	v_lshl_add_u64 v[242:243], v[130:131], 0, s[62:63]
	v_lshl_add_u64 v[244:245], v[242:243], 0, s[46:47]
	s_mov_b32 m0, s16
	s_nop 0
	global_load_lds_dwordx4 v[244:245], off
	v_lshl_add_u64 v[244:245], v[138:139], 0, s[62:63]
	v_lshl_add_u64 v[246:247], v[244:245], 0, s[46:47]
	s_mov_b32 m0, s17
	s_nop 0
	global_load_lds_dwordx4 v[246:247], off
	v_lshl_add_u64 v[246:247], v[136:137], 0, s[62:63]
	v_lshl_add_u64 v[248:249], v[246:247], 0, s[46:47]
	s_mov_b32 m0, s14
	s_nop 0
	global_load_lds_dwordx4 v[248:249], off
	v_lshl_add_u64 v[248:249], v[132:133], 0, s[62:63]
	v_lshl_add_u64 v[250:251], v[248:249], 0, s[46:47]
	s_mov_b32 m0, s89
	s_nop 0
	global_load_lds_dwordx4 v[250:251], off
	v_lshl_add_u64 v[250:251], v[134:135], 0, s[62:63]
	v_lshl_add_u64 v[166:167], v[250:251], 0, s[46:47]
	s_mov_b32 m0, s90
	s_nop 0
	global_load_lds_dwordx4 v[166:167], off
	s_waitcnt vmcnt(8)
	s_waitcnt lgkmcnt(0)
	s_barrier
	s_setprio 1
	s_waitcnt lgkmcnt(0)
	v_mfma_f32_16x16x32_bf16 v[60:63], v[148:151], v[190:193], v[60:63]
	v_mfma_f32_16x16x32_bf16 v[56:59], v[156:159], v[190:193], v[56:59]
	v_mfma_f32_16x16x32_bf16 v[52:55], v[148:151], v[212:215], v[52:55]
	v_mfma_f32_16x16x32_bf16 v[48:51], v[156:159], v[212:215], v[48:51]
	v_mfma_f32_16x16x32_bf16 v[44:47], v[148:151], v[220:223], v[44:47]
	v_mfma_f32_16x16x32_bf16 v[40:43], v[156:159], v[220:223], v[40:43]
	v_mfma_f32_16x16x32_bf16 v[36:39], v[148:151], v[228:231], v[36:39]
	v_mfma_f32_16x16x32_bf16 v[32:35], v[156:159], v[228:231], v[32:35]
	s_setprio 0
	s_setprio 1
	v_mfma_f32_16x16x32_bf16 v[60:63], v[152:155], v[208:211], v[60:63]
	v_mfma_f32_16x16x32_bf16 v[56:59], v[160:163], v[208:211], v[56:59]
	v_mfma_f32_16x16x32_bf16 v[52:55], v[152:155], v[216:219], v[52:55]
	v_mfma_f32_16x16x32_bf16 v[48:51], v[160:163], v[216:219], v[48:51]
	v_mfma_f32_16x16x32_bf16 v[44:47], v[152:155], v[224:227], v[44:47]
	v_mfma_f32_16x16x32_bf16 v[40:43], v[160:163], v[224:227], v[40:43]
	v_mfma_f32_16x16x32_bf16 v[36:39], v[152:155], v[232:235], v[36:39]
	v_mfma_f32_16x16x32_bf16 v[32:35], v[160:163], v[232:235], v[32:35]
	s_setprio 0
	s_setprio 1
	v_mfma_f32_16x16x32_bf16 v[28:31], v[174:177], v[190:193], v[28:31]
	v_mfma_f32_16x16x32_bf16 v[24:27], v[182:185], v[190:193], v[24:27]
	v_mfma_f32_16x16x32_bf16 v[20:23], v[174:177], v[212:215], v[20:23]
	v_mfma_f32_16x16x32_bf16 v[16:19], v[182:185], v[212:215], v[16:19]
	v_mfma_f32_16x16x32_bf16 v[12:15], v[174:177], v[220:223], v[12:15]
	v_mfma_f32_16x16x32_bf16 v[8:11], v[182:185], v[220:223], v[8:11]
	v_mfma_f32_16x16x32_bf16 v[4:7], v[174:177], v[228:231], v[4:7]
	v_mfma_f32_16x16x32_bf16 v[0:3], v[182:185], v[228:231], v[0:3]
	s_setprio 0
	s_setprio 1
	v_mfma_f32_16x16x32_bf16 v[28:31], v[178:181], v[208:211], v[28:31]
	v_mfma_f32_16x16x32_bf16 v[24:27], v[186:189], v[208:211], v[24:27]
	v_mfma_f32_16x16x32_bf16 v[20:23], v[178:181], v[216:219], v[20:23]
	v_mfma_f32_16x16x32_bf16 v[16:19], v[186:189], v[216:219], v[16:19]
	v_mfma_f32_16x16x32_bf16 v[12:15], v[178:181], v[224:227], v[12:15]
	v_mfma_f32_16x16x32_bf16 v[8:11], v[186:189], v[224:227], v[8:11]
	v_mfma_f32_16x16x32_bf16 v[4:7], v[178:181], v[232:235], v[4:7]
	v_mfma_f32_16x16x32_bf16 v[0:3], v[186:189], v[232:235], v[0:3]
	s_setprio 0
	s_barrier
	ds_read_b128 v[148:151], v146
	ds_read_b128 v[152:155], v146 offset:1024
	ds_read_b128 v[156:159], v146 offset:2048
	ds_read_b128 v[160:163], v146 offset:3072
	ds_read_b128 v[174:177], v147
	ds_read_b128 v[178:181], v147 offset:1024
	ds_read_b128 v[182:185], v147 offset:2048
	ds_read_b128 v[186:189], v147 offset:3072
	s_mov_b32 m0, s91
	v_lshl_add_u64 v[166:167], v[236:237], 0, s[46:47]
	ds_read_b128 v[190:193], v195 offset:32768
	ds_read_b128 v[208:211], v195 offset:33792
	ds_read_b128 v[212:215], v195 offset:34816
	ds_read_b128 v[216:219], v195 offset:35840
	ds_read_b128 v[220:223], v195 offset:36864
	ds_read_b128 v[224:227], v195 offset:37888
	ds_read_b128 v[228:231], v195 offset:38912
	ds_read_b128 v[232:235], v195 offset:39936
	global_load_lds_dwordx4 v[166:167], off
	v_lshl_add_u64 v[166:167], v[238:239], 0, s[46:47]
	s_mov_b32 m0, s92
	s_nop 0
	global_load_lds_dwordx4 v[166:167], off
	s_waitcnt vmcnt(8)
	s_waitcnt lgkmcnt(0)
	s_barrier
	s_setprio 1
	s_waitcnt lgkmcnt(0)
	v_mfma_f32_16x16x32_bf16 v[124:127], v[148:151], v[190:193], v[124:127]
	v_mfma_f32_16x16x32_bf16 v[120:123], v[156:159], v[190:193], v[120:123]
	v_mfma_f32_16x16x32_bf16 v[116:119], v[148:151], v[212:215], v[116:119]
	v_mfma_f32_16x16x32_bf16 v[112:115], v[156:159], v[212:215], v[112:115]
	v_mfma_f32_16x16x32_bf16 v[108:111], v[148:151], v[220:223], v[108:111]
	v_mfma_f32_16x16x32_bf16 v[104:107], v[156:159], v[220:223], v[104:107]
	v_mfma_f32_16x16x32_bf16 v[100:103], v[148:151], v[228:231], v[100:103]
	v_mfma_f32_16x16x32_bf16 v[96:99], v[156:159], v[228:231], v[96:99]
	s_setprio 0
	s_setprio 1
	v_mfma_f32_16x16x32_bf16 v[124:127], v[152:155], v[208:211], v[124:127]
	v_mfma_f32_16x16x32_bf16 v[120:123], v[160:163], v[208:211], v[120:123]
	v_mfma_f32_16x16x32_bf16 v[116:119], v[152:155], v[216:219], v[116:119]
	v_mfma_f32_16x16x32_bf16 v[112:115], v[160:163], v[216:219], v[112:115]
	v_mfma_f32_16x16x32_bf16 v[108:111], v[152:155], v[224:227], v[108:111]
	v_mfma_f32_16x16x32_bf16 v[104:107], v[160:163], v[224:227], v[104:107]
	v_mfma_f32_16x16x32_bf16 v[100:103], v[152:155], v[232:235], v[100:103]
	v_mfma_f32_16x16x32_bf16 v[96:99], v[160:163], v[232:235], v[96:99]
	s_setprio 0
	s_setprio 1
	v_mfma_f32_16x16x32_bf16 v[92:95], v[174:177], v[190:193], v[92:95]
	v_mfma_f32_16x16x32_bf16 v[88:91], v[182:185], v[190:193], v[88:91]
	v_mfma_f32_16x16x32_bf16 v[84:87], v[174:177], v[212:215], v[84:87]
	v_mfma_f32_16x16x32_bf16 v[80:83], v[182:185], v[212:215], v[80:83]
	v_mfma_f32_16x16x32_bf16 v[76:79], v[174:177], v[220:223], v[76:79]
	v_mfma_f32_16x16x32_bf16 v[72:75], v[182:185], v[220:223], v[72:75]
	v_mfma_f32_16x16x32_bf16 v[68:71], v[174:177], v[228:231], v[68:71]
	v_mfma_f32_16x16x32_bf16 v[64:67], v[182:185], v[228:231], v[64:67]
	s_setprio 0
	s_setprio 1
	v_mfma_f32_16x16x32_bf16 v[92:95], v[178:181], v[208:211], v[92:95]
	v_mfma_f32_16x16x32_bf16 v[88:91], v[186:189], v[208:211], v[88:91]
	v_mfma_f32_16x16x32_bf16 v[84:87], v[178:181], v[216:219], v[84:87]
	v_mfma_f32_16x16x32_bf16 v[80:83], v[186:189], v[216:219], v[80:83]
	v_mfma_f32_16x16x32_bf16 v[76:79], v[178:181], v[224:227], v[76:79]
	v_mfma_f32_16x16x32_bf16 v[72:75], v[186:189], v[224:227], v[72:75]
	v_mfma_f32_16x16x32_bf16 v[68:71], v[178:181], v[232:235], v[68:71]
	v_mfma_f32_16x16x32_bf16 v[64:67], v[186:189], v[232:235], v[64:67]
	s_setprio 0
	s_barrier
	s_mov_b32 m0, s15
	v_lshl_add_u64 v[166:167], v[240:241], 0, s[48:49]
	ds_read_b128 v[190:193], v195 offset:49152
	ds_read_b128 v[208:211], v195 offset:50176
	ds_read_b128 v[212:215], v195 offset:51200
	ds_read_b128 v[216:219], v195 offset:52224
	ds_read_b128 v[220:223], v195 offset:53248
	ds_read_b128 v[224:227], v195 offset:54272
	ds_read_b128 v[228:231], v195 offset:55296
	ds_read_b128 v[232:235], v195 offset:56320
	global_load_lds_dwordx4 v[166:167], off
	v_lshl_add_u64 v[166:167], v[242:243], 0, s[48:49]
	s_mov_b32 m0, s33
	s_nop 0
	global_load_lds_dwordx4 v[166:167], off
	v_lshl_add_u64 v[166:167], v[244:245], 0, s[48:49]
	s_mov_b32 m0, s3
	s_nop 0
	global_load_lds_dwordx4 v[166:167], off
	v_lshl_add_u64 v[166:167], v[246:247], 0, s[48:49]
	s_mov_b32 m0, s20
	s_nop 0
	global_load_lds_dwordx4 v[166:167], off
	v_lshl_add_u64 v[166:167], v[248:249], 0, s[48:49]
	s_mov_b32 m0, s93
	s_nop 0
	global_load_lds_dwordx4 v[166:167], off
	v_lshl_add_u64 v[166:167], v[250:251], 0, s[48:49]
	s_mov_b32 m0, s94
	s_nop 0
	global_load_lds_dwordx4 v[166:167], off
	s_waitcnt vmcnt(8)
	s_waitcnt lgkmcnt(0)
	s_barrier
	s_setprio 1
	s_waitcnt lgkmcnt(0)
	v_mfma_f32_16x16x32_bf16 v[60:63], v[148:151], v[190:193], v[60:63]
	v_mfma_f32_16x16x32_bf16 v[56:59], v[156:159], v[190:193], v[56:59]
	v_mfma_f32_16x16x32_bf16 v[52:55], v[148:151], v[212:215], v[52:55]
	v_mfma_f32_16x16x32_bf16 v[48:51], v[156:159], v[212:215], v[48:51]
	v_mfma_f32_16x16x32_bf16 v[44:47], v[148:151], v[220:223], v[44:47]
	v_mfma_f32_16x16x32_bf16 v[40:43], v[156:159], v[220:223], v[40:43]
	v_mfma_f32_16x16x32_bf16 v[36:39], v[148:151], v[228:231], v[36:39]
	v_mfma_f32_16x16x32_bf16 v[32:35], v[156:159], v[228:231], v[32:35]
	s_setprio 0
	s_setprio 1
	v_mfma_f32_16x16x32_bf16 v[60:63], v[152:155], v[208:211], v[60:63]
	v_mfma_f32_16x16x32_bf16 v[56:59], v[160:163], v[208:211], v[56:59]
	v_mfma_f32_16x16x32_bf16 v[52:55], v[152:155], v[216:219], v[52:55]
	v_mfma_f32_16x16x32_bf16 v[48:51], v[160:163], v[216:219], v[48:51]
	v_mfma_f32_16x16x32_bf16 v[44:47], v[152:155], v[224:227], v[44:47]
	v_mfma_f32_16x16x32_bf16 v[40:43], v[160:163], v[224:227], v[40:43]
	v_mfma_f32_16x16x32_bf16 v[36:39], v[152:155], v[232:235], v[36:39]
	v_mfma_f32_16x16x32_bf16 v[32:35], v[160:163], v[232:235], v[32:35]
	s_setprio 0
	s_setprio 1
	v_mfma_f32_16x16x32_bf16 v[28:31], v[174:177], v[190:193], v[28:31]
	v_mfma_f32_16x16x32_bf16 v[24:27], v[182:185], v[190:193], v[24:27]
	v_mfma_f32_16x16x32_bf16 v[20:23], v[174:177], v[212:215], v[20:23]
	s_add_u32 s62, s62, 0x100
	v_mfma_f32_16x16x32_bf16 v[16:19], v[182:185], v[212:215], v[16:19]
	s_addc_u32 s63, s63, 0
	v_mfma_f32_16x16x32_bf16 v[12:15], v[174:177], v[220:223], v[12:15]
	s_add_i32 s32, s22, 2
	v_mfma_f32_16x16x32_bf16 v[8:11], v[182:185], v[220:223], v[8:11]
	s_add_i32 s99, s22, -4
	v_mfma_f32_16x16x32_bf16 v[4:7], v[174:177], v[228:231], v[4:7]
	s_cmp_ge_i32 s99, s29
	v_mfma_f32_16x16x32_bf16 v[0:3], v[182:185], v[228:231], v[0:3]
	s_setprio 0
	s_setprio 1
	s_cselect_b32 s98, 0, 1
	v_mfma_f32_16x16x32_bf16 v[28:31], v[178:181], v[208:211], v[28:31]
	s_cmp_eq_u32 s34, s32
	v_mfma_f32_16x16x32_bf16 v[24:27], v[186:189], v[208:211], v[24:27]
	s_cselect_b64 vcc, -1, 0
	v_mfma_f32_16x16x32_bf16 v[20:23], v[178:181], v[216:219], v[20:23]
	s_and_b64 vcc, s[66:67], vcc
	v_mfma_f32_16x16x32_bf16 v[16:19], v[186:189], v[216:219], v[16:19]
	s_cselect_b32 s98, 0, s98
	v_mfma_f32_16x16x32_bf16 v[12:15], v[178:181], v[224:227], v[12:15]
	s_and_b64 vcc, exec, s[8:9]
	v_mfma_f32_16x16x32_bf16 v[8:11], v[186:189], v[224:227], v[8:11]
	s_cselect_b32 s98, s98, 0
	v_mfma_f32_16x16x32_bf16 v[4:7], v[178:181], v[232:235], v[4:7]
	s_cmp_lg_u32 s98, 0
	v_mfma_f32_16x16x32_bf16 v[0:3], v[186:189], v[232:235], v[0:3]
	s_setprio 0
	s_barrier
	s_cbranch_scc1 .Lk_fastb
	s_and_b64 vcc, exec, s[8:9]
	s_cbranch_vccnz .LBB0_394
	s_waitcnt vmcnt(16)
	v_mov_b32_e32 v148, s82
	v_mov_b32_e32 v149, s21
	ds_read_b32 v148, v148
	ds_read_b32 v149, v149 offset:60
	s_mov_b64 s[64:65], 0
	s_waitcnt lgkmcnt(0)
	v_readfirstlane_b32 s8, v148
	v_readfirstlane_b32 s9, v149
	s_mul_i32 s9, s9, s28
	s_cmp_lt_u32 s8, s9
	s_cbranch_scc1 .LBB0_394
	buffer_inv sc1
	s_mov_b64 s[64:65], -1

.LBB0_2163:
	ds_read_b128 v[150:153], v146
	ds_read_b128 v[154:157], v146 offset:1024
	ds_read_b128 v[158:161], v146 offset:2048
	ds_read_b128 v[162:165], v146 offset:3072
	ds_read_b128 v[166:169], v147
	ds_read_b128 v[180:183], v147 offset:1024
	ds_read_b128 v[184:187], v147 offset:2048
	ds_read_b128 v[188:191], v147 offset:3072
	v_lshl_add_u64 v[242:243], v[144:145], 0, s[38:39]
	s_mov_b32 m0, s95
	v_lshl_add_u64 v[244:245], v[242:243], 0, s[78:79]
	ds_read_b128 v[192:195], v200
	ds_read_b128 v[196:199], v200 offset:1024
	ds_read_b128 v[218:221], v200 offset:2048
	ds_read_b128 v[222:225], v200 offset:3072
	ds_read_b128 v[226:229], v200 offset:4096
	ds_read_b128 v[230:233], v200 offset:5120
	ds_read_b128 v[234:237], v200 offset:6144
	ds_read_b128 v[238:241], v200 offset:7168
	global_load_lds_dwordx4 v[244:245], off
	v_lshl_add_u64 v[244:245], v[142:143], 0, s[38:39]
	v_lshl_add_u64 v[246:247], v[244:245], 0, s[78:79]
	s_mov_b32 m0, s96
	s_nop 0
	global_load_lds_dwordx4 v[246:247], off
	s_waitcnt vmcnt(8)
	s_waitcnt lgkmcnt(0)
	s_barrier
	s_setprio 1
	s_waitcnt lgkmcnt(0)
	v_mfma_f32_16x16x32_bf16 v[126:129], v[150:153], v[192:195], v[126:129]
	v_mfma_f32_16x16x32_bf16 v[122:125], v[158:161], v[192:195], v[122:125]
	v_mfma_f32_16x16x32_bf16 v[118:121], v[150:153], v[218:221], v[118:121]
	v_mfma_f32_16x16x32_bf16 v[114:117], v[158:161], v[218:221], v[114:117]
	v_mfma_f32_16x16x32_bf16 v[110:113], v[150:153], v[226:229], v[110:113]
	v_mfma_f32_16x16x32_bf16 v[106:109], v[158:161], v[226:229], v[106:109]
	v_mfma_f32_16x16x32_bf16 v[102:105], v[150:153], v[234:237], v[102:105]
	v_mfma_f32_16x16x32_bf16 v[98:101], v[158:161], v[234:237], v[98:101]
	s_setprio 0
	s_setprio 1
	v_mfma_f32_16x16x32_bf16 v[126:129], v[154:157], v[196:199], v[126:129]
	v_mfma_f32_16x16x32_bf16 v[122:125], v[162:165], v[196:199], v[122:125]
	v_mfma_f32_16x16x32_bf16 v[118:121], v[154:157], v[222:225], v[118:121]
	v_mfma_f32_16x16x32_bf16 v[114:117], v[162:165], v[222:225], v[114:117]
	v_mfma_f32_16x16x32_bf16 v[110:113], v[154:157], v[230:233], v[110:113]
	v_mfma_f32_16x16x32_bf16 v[106:109], v[162:165], v[230:233], v[106:109]
	v_mfma_f32_16x16x32_bf16 v[102:105], v[154:157], v[238:241], v[102:105]
	v_mfma_f32_16x16x32_bf16 v[98:101], v[162:165], v[238:241], v[98:101]
	s_setprio 0
	s_setprio 1
	v_mfma_f32_16x16x32_bf16 v[94:97], v[166:169], v[192:195], v[94:97]
	v_mfma_f32_16x16x32_bf16 v[90:93], v[184:187], v[192:195], v[90:93]
	v_mfma_f32_16x16x32_bf16 v[86:89], v[166:169], v[218:221], v[86:89]
	v_mfma_f32_16x16x32_bf16 v[82:85], v[184:187], v[218:221], v[82:85]
	v_mfma_f32_16x16x32_bf16 v[78:81], v[166:169], v[226:229], v[78:81]
	v_mfma_f32_16x16x32_bf16 v[74:77], v[184:187], v[226:229], v[74:77]
	v_mfma_f32_16x16x32_bf16 v[70:73], v[166:169], v[234:237], v[70:73]
	v_mfma_f32_16x16x32_bf16 v[66:69], v[184:187], v[234:237], v[66:69]
	s_setprio 0
	s_setprio 1
	v_mfma_f32_16x16x32_bf16 v[94:97], v[180:183], v[196:199], v[94:97]
	v_mfma_f32_16x16x32_bf16 v[90:93], v[188:191], v[196:199], v[90:93]
	v_mfma_f32_16x16x32_bf16 v[86:89], v[180:183], v[222:225], v[86:89]
	v_mfma_f32_16x16x32_bf16 v[82:85], v[188:191], v[222:225], v[82:85]
	v_mfma_f32_16x16x32_bf16 v[78:81], v[180:183], v[230:233], v[78:81]
	v_mfma_f32_16x16x32_bf16 v[74:77], v[188:191], v[230:233], v[74:77]
	v_mfma_f32_16x16x32_bf16 v[70:73], v[180:183], v[238:241], v[70:73]
	v_mfma_f32_16x16x32_bf16 v[66:69], v[188:191], v[238:241], v[66:69]
	s_setprio 0
	s_barrier
	v_lshl_add_u64 v[246:247], v[130:131], 0, s[38:39]
	s_mov_b32 m0, s2
	v_lshl_add_u64 v[248:249], v[246:247], 0, s[76:77]
	ds_read_b128 v[192:195], v200 offset:16384
	ds_read_b128 v[196:199], v200 offset:17408
	ds_read_b128 v[218:221], v200 offset:18432
	ds_read_b128 v[222:225], v200 offset:19456
	ds_read_b128 v[226:229], v200 offset:20480
	ds_read_b128 v[230:233], v200 offset:21504
	ds_read_b128 v[234:237], v200 offset:22528
	ds_read_b128 v[238:241], v200 offset:23552
	global_load_lds_dwordx4 v[248:249], off
	v_lshl_add_u64 v[248:249], v[132:133], 0, s[38:39]
	v_lshl_add_u64 v[250:251], v[248:249], 0, s[76:77]
	s_mov_b32 m0, s56
	s_nop 0
	global_load_lds_dwordx4 v[250:251], off
	v_lshl_add_u64 v[250:251], v[140:141], 0, s[38:39]
	v_lshl_add_u64 v[206:207], v[250:251], 0, s[76:77]
	s_mov_b32 m0, s19
	s_nop 0
	global_load_lds_dwordx4 v[206:207], off
	v_lshl_add_u64 v[206:207], v[138:139], 0, s[38:39]
	v_lshl_add_u64 v[204:205], v[206:207], 0, s[76:77]
	s_mov_b32 m0, s63
	s_nop 0
	global_load_lds_dwordx4 v[204:205], off
	v_lshl_add_u64 v[204:205], v[134:135], 0, s[38:39]
	v_lshl_add_u64 v[170:171], v[204:205], 0, s[76:77]
	s_mov_b32 m0, s53
	s_nop 0
	global_load_lds_dwordx4 v[170:171], off
	v_lshl_add_u64 v[170:171], v[136:137], 0, s[38:39]
	v_lshl_add_u64 v[208:209], v[170:171], 0, s[76:77]
	s_mov_b32 m0, s92
	s_nop 0
	global_load_lds_dwordx4 v[208:209], off
	s_waitcnt vmcnt(8)
	s_waitcnt lgkmcnt(0)
	s_barrier
	s_setprio 1
	s_waitcnt lgkmcnt(0)
	v_mfma_f32_16x16x32_bf16 v[62:65], v[150:153], v[192:195], v[62:65]
	v_mfma_f32_16x16x32_bf16 v[58:61], v[158:161], v[192:195], v[58:61]
	v_mfma_f32_16x16x32_bf16 v[54:57], v[150:153], v[218:221], v[54:57]
	v_mfma_f32_16x16x32_bf16 v[50:53], v[158:161], v[218:221], v[50:53]
	v_mfma_f32_16x16x32_bf16 v[46:49], v[150:153], v[226:229], v[46:49]
	v_mfma_f32_16x16x32_bf16 v[42:45], v[158:161], v[226:229], v[42:45]
	v_mfma_f32_16x16x32_bf16 v[38:41], v[150:153], v[234:237], v[38:41]
	v_mfma_f32_16x16x32_bf16 v[34:37], v[158:161], v[234:237], v[34:37]
	s_setprio 0
	s_setprio 1
	v_mfma_f32_16x16x32_bf16 v[62:65], v[154:157], v[196:199], v[62:65]
	v_mfma_f32_16x16x32_bf16 v[58:61], v[162:165], v[196:199], v[58:61]
	v_mfma_f32_16x16x32_bf16 v[54:57], v[154:157], v[222:225], v[54:57]
	v_mfma_f32_16x16x32_bf16 v[50:53], v[162:165], v[222:225], v[50:53]
	v_mfma_f32_16x16x32_bf16 v[46:49], v[154:157], v[230:233], v[46:49]
	v_mfma_f32_16x16x32_bf16 v[42:45], v[162:165], v[230:233], v[42:45]
	v_mfma_f32_16x16x32_bf16 v[38:41], v[154:157], v[238:241], v[38:41]
	v_mfma_f32_16x16x32_bf16 v[34:37], v[162:165], v[238:241], v[34:37]
	s_setprio 0
	s_setprio 1
	v_mfma_f32_16x16x32_bf16 v[30:33], v[166:169], v[192:195], v[30:33]
	v_mfma_f32_16x16x32_bf16 v[26:29], v[184:187], v[192:195], v[26:29]
	v_mfma_f32_16x16x32_bf16 v[22:25], v[166:169], v[218:221], v[22:25]
	v_mfma_f32_16x16x32_bf16 v[18:21], v[184:187], v[218:221], v[18:21]
	v_mfma_f32_16x16x32_bf16 v[14:17], v[166:169], v[226:229], v[14:17]
	v_mfma_f32_16x16x32_bf16 v[10:13], v[184:187], v[226:229], v[10:13]
	v_mfma_f32_16x16x32_bf16 v[6:9], v[166:169], v[234:237], v[6:9]
	v_mfma_f32_16x16x32_bf16 v[2:5], v[184:187], v[234:237], v[2:5]
	s_setprio 0
	s_setprio 1
	v_mfma_f32_16x16x32_bf16 v[30:33], v[180:183], v[196:199], v[30:33]
	v_mfma_f32_16x16x32_bf16 v[26:29], v[188:191], v[196:199], v[26:29]
	v_mfma_f32_16x16x32_bf16 v[22:25], v[180:183], v[222:225], v[22:25]
	v_mfma_f32_16x16x32_bf16 v[18:21], v[188:191], v[222:225], v[18:21]
	v_mfma_f32_16x16x32_bf16 v[14:17], v[180:183], v[230:233], v[14:17]
	v_mfma_f32_16x16x32_bf16 v[10:13], v[188:191], v[230:233], v[10:13]
	v_mfma_f32_16x16x32_bf16 v[6:9], v[180:183], v[238:241], v[6:9]
	v_mfma_f32_16x16x32_bf16 v[2:5], v[188:191], v[238:241], v[2:5]
	s_setprio 0
	s_barrier
	ds_read_b128 v[150:153], v148
	ds_read_b128 v[154:157], v148 offset:1024
	ds_read_b128 v[158:161], v148 offset:2048
	ds_read_b128 v[162:165], v148 offset:3072
	ds_read_b128 v[166:169], v149
	ds_read_b128 v[180:183], v149 offset:1024
	ds_read_b128 v[184:187], v149 offset:2048
	ds_read_b128 v[188:191], v149 offset:3072
	s_mov_b32 m0, s93
	v_lshl_add_u64 v[208:209], v[242:243], 0, s[76:77]
	ds_read_b128 v[192:195], v200 offset:32768
	ds_read_b128 v[196:199], v200 offset:33792
	ds_read_b128 v[218:221], v200 offset:34816
	ds_read_b128 v[222:225], v200 offset:35840
	ds_read_b128 v[226:229], v200 offset:36864
	ds_read_b128 v[230:233], v200 offset:37888
	ds_read_b128 v[234:237], v200 offset:38912
	ds_read_b128 v[238:241], v200 offset:39936
	global_load_lds_dwordx4 v[208:209], off
	v_lshl_add_u64 v[208:209], v[244:245], 0, s[76:77]
	s_mov_b32 m0, s54
	s_nop 0
	global_load_lds_dwordx4 v[208:209], off
	s_waitcnt vmcnt(8)
	s_waitcnt lgkmcnt(0)
	s_barrier
	s_setprio 1
	s_waitcnt lgkmcnt(0)
	v_mfma_f32_16x16x32_bf16 v[126:129], v[150:153], v[192:195], v[126:129]
	v_mfma_f32_16x16x32_bf16 v[122:125], v[158:161], v[192:195], v[122:125]
	v_mfma_f32_16x16x32_bf16 v[118:121], v[150:153], v[218:221], v[118:121]
	v_mfma_f32_16x16x32_bf16 v[114:117], v[158:161], v[218:221], v[114:117]
	v_mfma_f32_16x16x32_bf16 v[110:113], v[150:153], v[226:229], v[110:113]
	v_mfma_f32_16x16x32_bf16 v[106:109], v[158:161], v[226:229], v[106:109]
	v_mfma_f32_16x16x32_bf16 v[102:105], v[150:153], v[234:237], v[102:105]
	v_mfma_f32_16x16x32_bf16 v[98:101], v[158:161], v[234:237], v[98:101]
	s_setprio 0
	s_setprio 1
	v_mfma_f32_16x16x32_bf16 v[126:129], v[154:157], v[196:199], v[126:129]
	v_mfma_f32_16x16x32_bf16 v[122:125], v[162:165], v[196:199], v[122:125]
	v_mfma_f32_16x16x32_bf16 v[118:121], v[154:157], v[222:225], v[118:121]
	v_mfma_f32_16x16x32_bf16 v[114:117], v[162:165], v[222:225], v[114:117]
	v_mfma_f32_16x16x32_bf16 v[110:113], v[154:157], v[230:233], v[110:113]
	v_mfma_f32_16x16x32_bf16 v[106:109], v[162:165], v[230:233], v[106:109]
	v_mfma_f32_16x16x32_bf16 v[102:105], v[154:157], v[238:241], v[102:105]
	v_mfma_f32_16x16x32_bf16 v[98:101], v[162:165], v[238:241], v[98:101]
	s_setprio 0
	s_setprio 1
	v_mfma_f32_16x16x32_bf16 v[94:97], v[166:169], v[192:195], v[94:97]
	v_mfma_f32_16x16x32_bf16 v[90:93], v[184:187], v[192:195], v[90:93]
	v_mfma_f32_16x16x32_bf16 v[86:89], v[166:169], v[218:221], v[86:89]
	v_mfma_f32_16x16x32_bf16 v[82:85], v[184:187], v[218:221], v[82:85]
	v_mfma_f32_16x16x32_bf16 v[78:81], v[166:169], v[226:229], v[78:81]
	v_mfma_f32_16x16x32_bf16 v[74:77], v[184:187], v[226:229], v[74:77]
	v_mfma_f32_16x16x32_bf16 v[70:73], v[166:169], v[234:237], v[70:73]
	v_mfma_f32_16x16x32_bf16 v[66:69], v[184:187], v[234:237], v[66:69]
	s_setprio 0
	s_setprio 1
	v_mfma_f32_16x16x32_bf16 v[94:97], v[180:183], v[196:199], v[94:97]
	v_mfma_f32_16x16x32_bf16 v[90:93], v[188:191], v[196:199], v[90:93]
	v_mfma_f32_16x16x32_bf16 v[86:89], v[180:183], v[222:225], v[86:89]
	v_mfma_f32_16x16x32_bf16 v[82:85], v[188:191], v[222:225], v[82:85]
	v_mfma_f32_16x16x32_bf16 v[78:81], v[180:183], v[230:233], v[78:81]
	v_mfma_f32_16x16x32_bf16 v[74:77], v[188:191], v[230:233], v[74:77]
	v_mfma_f32_16x16x32_bf16 v[70:73], v[180:183], v[238:241], v[70:73]
	v_mfma_f32_16x16x32_bf16 v[66:69], v[188:191], v[238:241], v[66:69]
	s_setprio 0
	s_barrier
	s_mov_b32 m0, s33
	v_lshl_add_u64 v[208:209], v[246:247], 0, s[80:81]
	ds_read_b128 v[192:195], v200 offset:49152
	ds_read_b128 v[196:199], v200 offset:50176
	ds_read_b128 v[218:221], v200 offset:51200
	ds_read_b128 v[222:225], v200 offset:52224
	ds_read_b128 v[226:229], v200 offset:53248
	ds_read_b128 v[230:233], v200 offset:54272
	ds_read_b128 v[234:237], v200 offset:55296
	ds_read_b128 v[238:241], v200 offset:56320
	global_load_lds_dwordx4 v[208:209], off
	v_lshl_add_u64 v[208:209], v[248:249], 0, s[80:81]
	s_mov_b32 m0, s3
	v_lshl_add_u64 v[206:207], v[206:207], 0, s[80:81]
	global_load_lds_dwordx4 v[208:209], off
	v_lshl_add_u64 v[208:209], v[250:251], 0, s[80:81]
	s_mov_b32 m0, s47
	v_lshl_add_u64 v[204:205], v[204:205], 0, s[80:81]
	global_load_lds_dwordx4 v[208:209], off
	s_mov_b32 m0, s4
	v_lshl_add_u64 v[170:171], v[170:171], 0, s[80:81]
	global_load_lds_dwordx4 v[206:207], off
	s_mov_b32 m0, s55
	s_nop 0
	global_load_lds_dwordx4 v[204:205], off
	s_mov_b32 m0, s64
	s_nop 0
	global_load_lds_dwordx4 v[170:171], off
	s_waitcnt vmcnt(8)
	s_waitcnt lgkmcnt(0)
	s_barrier
	s_setprio 1
	s_waitcnt lgkmcnt(0)
	v_mfma_f32_16x16x32_bf16 v[62:65], v[150:153], v[192:195], v[62:65]
	v_mfma_f32_16x16x32_bf16 v[58:61], v[158:161], v[192:195], v[58:61]
	v_mfma_f32_16x16x32_bf16 v[54:57], v[150:153], v[218:221], v[54:57]
	v_mfma_f32_16x16x32_bf16 v[50:53], v[158:161], v[218:221], v[50:53]
	v_mfma_f32_16x16x32_bf16 v[46:49], v[150:153], v[226:229], v[46:49]
	v_mfma_f32_16x16x32_bf16 v[42:45], v[158:161], v[226:229], v[42:45]
	v_mfma_f32_16x16x32_bf16 v[38:41], v[150:153], v[234:237], v[38:41]
	v_mfma_f32_16x16x32_bf16 v[34:37], v[158:161], v[234:237], v[34:37]
	s_setprio 0
	s_setprio 1
	v_mfma_f32_16x16x32_bf16 v[62:65], v[154:157], v[196:199], v[62:65]
	v_mfma_f32_16x16x32_bf16 v[58:61], v[162:165], v[196:199], v[58:61]
	v_mfma_f32_16x16x32_bf16 v[54:57], v[154:157], v[222:225], v[54:57]
	v_mfma_f32_16x16x32_bf16 v[50:53], v[162:165], v[222:225], v[50:53]
	v_mfma_f32_16x16x32_bf16 v[46:49], v[154:157], v[230:233], v[46:49]
	v_mfma_f32_16x16x32_bf16 v[42:45], v[162:165], v[230:233], v[42:45]
	v_mfma_f32_16x16x32_bf16 v[38:41], v[154:157], v[238:241], v[38:41]
	v_mfma_f32_16x16x32_bf16 v[34:37], v[162:165], v[238:241], v[34:37]
	s_setprio 0
	s_setprio 1
	v_mfma_f32_16x16x32_bf16 v[30:33], v[166:169], v[192:195], v[30:33]
	v_mfma_f32_16x16x32_bf16 v[26:29], v[184:187], v[192:195], v[26:29]
	v_mfma_f32_16x16x32_bf16 v[22:25], v[166:169], v[218:221], v[22:25]
	s_add_u32 s38, s38, 0x100
	v_mfma_f32_16x16x32_bf16 v[18:21], v[184:187], v[218:221], v[18:21]
	s_addc_u32 s39, s39, 0
	v_mfma_f32_16x16x32_bf16 v[14:17], v[166:169], v[226:229], v[14:17]
	s_add_i32 s32, s62, 2
	v_mfma_f32_16x16x32_bf16 v[10:13], v[184:187], v[226:229], v[10:13]
	s_add_i32 s99, s62, -4
	v_mfma_f32_16x16x32_bf16 v[6:9], v[166:169], v[234:237], v[6:9]
	s_cmp_ge_i32 s99, s51
	v_mfma_f32_16x16x32_bf16 v[2:5], v[184:187], v[234:237], v[2:5]
	s_setprio 0
	s_setprio 1
	s_cselect_b32 s98, 0, 1
	v_mfma_f32_16x16x32_bf16 v[30:33], v[180:183], v[196:199], v[30:33]
	s_cmp_eq_u32 s94, s32
	v_mfma_f32_16x16x32_bf16 v[26:29], v[188:191], v[196:199], v[26:29]
	s_cselect_b64 vcc, -1, 0
	v_mfma_f32_16x16x32_bf16 v[22:25], v[180:183], v[222:225], v[22:25]
	s_and_b64 vcc, s[16:17], vcc
	v_mfma_f32_16x16x32_bf16 v[18:21], v[188:191], v[222:225], v[18:21]
	s_cselect_b32 s98, 0, s98
	v_mfma_f32_16x16x32_bf16 v[14:17], v[180:183], v[230:233], v[14:17]
	s_and_b64 vcc, exec, s[10:11]
	v_mfma_f32_16x16x32_bf16 v[10:13], v[188:191], v[230:233], v[10:13]
	s_cselect_b32 s98, s98, 0
	v_mfma_f32_16x16x32_bf16 v[6:9], v[180:183], v[238:241], v[6:9]
	s_cmp_lg_u32 s98, 0
	v_mfma_f32_16x16x32_bf16 v[2:5], v[188:191], v[238:241], v[2:5]
	s_setprio 0
	s_barrier
	s_cbranch_scc1 .Lk_fasta
	s_and_b64 vcc, exec, s[10:11]
	s_cbranch_vccnz .LBB0_2166
	s_waitcnt vmcnt(16)
	v_mov_b32_e32 v150, s50
	v_mov_b32_e32 v151, s5
	ds_read_b32 v150, v150
	ds_read_b32 v151, v151 offset:60
	s_mov_b64 s[40:41], 0
	s_waitcnt lgkmcnt(0)
	v_readfirstlane_b32 s10, v150
	v_readfirstlane_b32 s11, v151
	s_mul_i32 s11, s11, s18
	s_cmp_lt_u32 s10, s11
	s_cbranch_scc1 .LBB0_2166
	buffer_inv sc1
	s_mov_b64 s[40:41], -1
